# drop buffer_wbl2 from XCC-local barrier leader path
# speedup vs baseline: 1.0037x; 1.0037x over previous
; DI unsigned xb_add(unsigned* p, unsigned v) { return __hip_atomic_fetch_add(p, v, __ATOMIC_RELAXED, __HIP_MEMORY_SCOPE_AGENT); }
; DI void xcd_barrier_local(const XcdBarrier& b) {
;     ...
;         if (old + 1u == (gen + 1u) * nloc) {
;             __builtin_amdgcn_fence(__ATOMIC_RELEASE, "agent");
;             asm volatile("s_waitcnt vmcnt(0)" ::: "memory");
;             __builtin_amdgcn_fence(__ATOMIC_ACQUIRE, "agent");
;             xb_add(&bar[XB_XGEN(b.x)], 1u);
;             asm volatile("s_waitcnt vmcnt(0)" ::: "memory");
.LBB0_648:
	s_andn2_saveexec_b64 s[4:5], s[16:17]
	s_cbranch_execz .LBB0_650
	v_readlane_b32 s4, v254, 42
	v_readlane_b32 s5, v254, 43
	s_waitcnt vmcnt(0)
	buffer_inv sc1
	s_nop 2
	global_atomic_add v97, v189, s[4:5]
	s_waitcnt vmcnt(0)
